# v109 + attention row-sum chains: removed the x+0 no-op add (1 VALU per half-block)
# speedup vs baseline: 1.0035x; 1.0014x over previous
.LBB0_272:
	v_add_u32_e32 v197, s62, v240
	ds_read_b64_tr_b16 v[188:189], v197 offset:24576
	ds_read_b64_tr_b16 v[190:191], v197 offset:25088
	s_waitcnt lgkmcnt(11)
	v_mfma_f32_32x32x16_bf16 v[80:95], v[184:187], v[128:131], 0
	v_add_f32_e32 v64, v48, v49
	v_add_f32_e32 v64, v50, v64
	v_add_f32_e32 v64, v51, v64
	v_add_f32_e32 v64, v52, v64
	v_add_f32_e32 v64, v53, v64
	v_cvt_pk_bf16_f32 v144, v48, v49
	v_cvt_pk_bf16_f32 v145, v50, v51
	ds_read_b64_tr_b16 v[184:185], v197 offset:28672
	ds_read_b64_tr_b16 v[186:187], v197 offset:29184
	v_add_f32_e32 v48, v54, v64
	s_waitcnt lgkmcnt(12)
	v_mfma_f32_32x32x16_bf16 v[64:79], v[176:179], v[128:131], 0
	v_add_f32_e32 v48, v55, v48
	v_add_f32_e32 v48, v56, v48
	v_add_f32_e32 v132, v57, v48
	v_cvt_pk_bf16_f32 v146, v52, v53
	v_cvt_pk_bf16_f32 v147, v54, v55
	ds_read_b64_tr_b16 v[48:49], v197 offset:25600
	ds_read_b64_tr_b16 v[50:51], v197 offset:26112
	s_waitcnt lgkmcnt(11)
	v_mfma_f32_32x32x16_bf16 v[80:95], v[180:183], v[124:127], v[80:95]
	v_add_f32_e32 v52, v58, v132
	v_add_f32_e32 v52, v59, v52
	v_add_f32_e32 v52, v60, v52
	v_add_f32_e32 v132, v61, v52
	v_cvt_pk_bf16_f32 v140, v56, v57
	v_cvt_pk_bf16_f32 v141, v58, v59
	ds_read_b64_tr_b16 v[52:53], v197 offset:29696
	ds_read_b64_tr_b16 v[54:55], v197 offset:30208
	s_waitcnt lgkmcnt(12)
	v_mfma_f32_32x32x16_bf16 v[64:79], v[172:175], v[124:127], v[64:79]
	v_add_f32_e32 v56, v62, v132
	v_add_f32_e32 v56, v63, v56
	v_add_f32_e32 v56, v32, v56
	v_add_f32_e32 v132, v33, v56
	v_cvt_pk_bf16_f32 v142, v60, v61
	v_cvt_pk_bf16_f32 v143, v62, v63
	ds_read_b64_tr_b16 v[56:57], v197 offset:26624
	ds_read_b64_tr_b16 v[58:59], v197 offset:27136
	s_waitcnt lgkmcnt(13)
	v_mfma_f32_32x32x16_bf16 v[80:95], v[168:171], v[120:123], v[80:95]
	v_add_f32_e32 v60, v34, v132
	v_add_f32_e32 v60, v35, v60
	v_add_f32_e32 v60, v36, v60
	v_add_f32_e32 v60, v37, v60
	v_cvt_pk_bf16_f32 v136, v32, v33
	v_cvt_pk_bf16_f32 v137, v34, v35
	ds_read_b64_tr_b16 v[32:33], v197 offset:30720
	ds_read_b64_tr_b16 v[34:35], v197 offset:31232
	s_waitcnt lgkmcnt(14)
	v_mfma_f32_32x32x16_bf16 v[64:79], v[164:167], v[120:123], v[64:79]
	v_add_f32_e32 v60, v38, v60
	v_add_f32_e32 v60, v39, v60
	v_add_f32_e32 v60, v40, v60
	v_add_f32_e32 v60, v41, v60
	v_cvt_pk_bf16_f32 v138, v36, v37
	v_cvt_pk_bf16_f32 v139, v38, v39
	ds_read_b64_tr_b16 v[36:37], v197 offset:27648
	ds_read_b64_tr_b16 v[38:39], v197 offset:28160
	s_waitcnt lgkmcnt(14)
	v_mfma_f32_32x32x16_bf16 v[80:95], v[160:163], v[116:119], v[80:95]
	v_add_f32_e32 v60, v42, v60
	v_add_f32_e32 v60, v43, v60
	v_add_f32_e32 v60, v44, v60
	v_add_f32_e32 v60, v45, v60
	v_cvt_pk_bf16_f32 v132, v40, v41
	v_cvt_pk_bf16_f32 v133, v42, v43
	ds_read_b64_tr_b16 v[40:41], v197 offset:31744
	ds_read_b64_tr_b16 v[42:43], v197 offset:32256
	v_mfma_f32_32x32x16_bf16 v[64:79], v[156:159], v[116:119], v[64:79]
	v_add_f32_e32 v60, v46, v60
	v_add_f32_e32 v60, v47, v60
	v_cvt_pk_bf16_f32 v134, v44, v45
	v_cvt_pk_bf16_f32 v135, v46, v47
	v_mfma_f32_32x32x16_bf16 v[80:95], v[152:155], v[96:99], v[80:95]
	v_lshl_add_u64 v[214:215], v[212:213], 0, s[20:21]
	v_lshl_add_u64 v[44:45], v[214:215], 0, s[28:29]
	v_lshl_add_u64 v[216:217], v[198:199], 0, s[20:21]
	s_add_i32 s43, s68, s97
	s_mov_b32 s46, m0
	s_mov_b32 m0, s43
	s_nop 0
	global_load_lds_dwordx4 v[44:45], off
	s_mov_b32 m0, s46
	v_lshl_add_u64 v[44:45], v[216:217], 0, s[30:31]
	s_add_i32 s43, s47, s70
	v_mfma_f32_32x32x16_bf16 v[64:79], v[148:151], v[96:99], v[64:79]
	s_mov_b32 s46, m0
	s_mov_b32 m0, s43
	s_nop 0
	global_load_lds_dwordx4 v[44:45], off
	s_mov_b32 m0, s46
	s_nop 4
	v_max_f32_e32 v44, v80, v81
	v_add_f32_e32 v197, v243, v60
	s_nop 2
	v_max3_f32 v45, v82, v83, v65
	v_max3_f32 v44, v44, v64, v66
	v_max3_f32 v44, v44, v67, v84
	v_max3_f32 v45, v45, v86, v87
	v_max3_f32 v44, v44, v85, v68
	v_max3_f32 v45, v45, v70, v71
	v_max3_f32 v44, v44, v69, v88
	v_max3_f32 v45, v45, v90, v91
	v_max3_f32 v44, v44, v89, v72
	v_max3_f32 v45, v45, v74, v75
	v_max3_f32 v44, v44, v73, v92
	v_max3_f32 v45, v45, v94, v95
	v_max3_f32 v44, v44, v93, v76
	v_max3_f32 v45, v45, v78, v79
	v_max3_f32 v44, v44, v77, v45
	v_mov_b32_e32 v45, v44
	s_nop 1
	v_permlane32_swap_b32_e32 v44, v45
	v_max_f32_e32 v44, v44, v45
	v_cmp_lt_f32_e32 vcc, s84, v44
	s_cmp_lg_u64 vcc, 0
	s_cselect_b64 s[62:63], -1, 0
	s_cbranch_vccnz .LBB0_280

.LBB0_275:
	s_add_i32 s43, s47, 0x2000
	s_cmpk_lg_i32 s47, 0x4000
	s_cselect_b32 s43, s43, 0
	v_add_u32_e32 v190, s68, v240
	ds_read_b64_tr_b16 v[160:161], v190 offset:24576
	ds_read_b64_tr_b16 v[162:163], v190 offset:25088
	s_waitcnt lgkmcnt(11)
	v_mfma_f32_32x32x16_bf16 v[48:63], v[60:63], v[128:131], 0
	v_add_f32_e32 v32, v80, v81
	v_add_f32_e32 v32, v82, v32
	v_add_f32_e32 v32, v83, v32
	v_add_f32_e32 v32, v84, v32
	v_add_f32_e32 v32, v85, v32
	v_cvt_pk_bf16_f32 v144, v80, v81
	v_cvt_pk_bf16_f32 v145, v82, v83
	ds_read_b64_tr_b16 v[156:157], v190 offset:28672
	ds_read_b64_tr_b16 v[158:159], v190 offset:29184
	v_add_f32_e32 v32, v86, v32
	v_add_f32_e32 v32, v87, v32
	v_add_f32_e32 v32, v88, v32
	v_add_f32_e32 v132, v89, v32
	s_waitcnt lgkmcnt(12)
	v_mfma_f32_32x32x16_bf16 v[32:47], v[44:47], v[128:131], 0
	v_cvt_pk_bf16_f32 v146, v84, v85
	v_cvt_pk_bf16_f32 v147, v86, v87
	ds_read_b64_tr_b16 v[80:81], v190 offset:25600
	ds_read_b64_tr_b16 v[82:83], v190 offset:26112
	s_waitcnt lgkmcnt(11)
	v_mfma_f32_32x32x16_bf16 v[48:63], v[184:187], v[124:127], v[48:63]
	v_add_f32_e32 v84, v90, v132
	v_add_f32_e32 v84, v91, v84
	v_add_f32_e32 v84, v92, v84
	v_add_f32_e32 v132, v93, v84
	v_cvt_pk_bf16_f32 v140, v88, v89
	v_cvt_pk_bf16_f32 v141, v90, v91
	ds_read_b64_tr_b16 v[84:85], v190 offset:29696
	ds_read_b64_tr_b16 v[86:87], v190 offset:30208
	s_waitcnt lgkmcnt(12)
	v_mfma_f32_32x32x16_bf16 v[32:47], v[180:183], v[124:127], v[32:47]
	v_add_f32_e32 v88, v94, v132
	v_add_f32_e32 v88, v95, v88
	v_add_f32_e32 v88, v64, v88
	v_add_f32_e32 v132, v65, v88
	v_cvt_pk_bf16_f32 v142, v92, v93
	v_cvt_pk_bf16_f32 v143, v94, v95
	ds_read_b64_tr_b16 v[88:89], v190 offset:26624
	ds_read_b64_tr_b16 v[90:91], v190 offset:27136
	s_waitcnt lgkmcnt(13)
	v_mfma_f32_32x32x16_bf16 v[48:63], v[176:179], v[120:123], v[48:63]
	v_add_f32_e32 v92, v66, v132
	v_add_f32_e32 v92, v67, v92
	v_add_f32_e32 v92, v68, v92
	v_add_f32_e32 v92, v69, v92
	v_cvt_pk_bf16_f32 v136, v64, v65
	v_cvt_pk_bf16_f32 v137, v66, v67
	ds_read_b64_tr_b16 v[64:65], v190 offset:30720
	ds_read_b64_tr_b16 v[66:67], v190 offset:31232
	s_waitcnt lgkmcnt(14)
	v_mfma_f32_32x32x16_bf16 v[32:47], v[172:175], v[120:123], v[32:47]
	v_add_f32_e32 v92, v70, v92
	v_add_f32_e32 v92, v71, v92
	v_add_f32_e32 v92, v72, v92
	v_add_f32_e32 v92, v73, v92
	v_cvt_pk_bf16_f32 v138, v68, v69
	v_cvt_pk_bf16_f32 v139, v70, v71
	ds_read_b64_tr_b16 v[68:69], v190 offset:27648
	ds_read_b64_tr_b16 v[70:71], v190 offset:28160
	s_waitcnt lgkmcnt(14)
	v_mfma_f32_32x32x16_bf16 v[48:63], v[168:171], v[116:119], v[48:63]
	v_add_f32_e32 v92, v74, v92
	v_add_f32_e32 v92, v75, v92
	v_add_f32_e32 v92, v76, v92
	v_add_f32_e32 v92, v77, v92
	v_cvt_pk_bf16_f32 v132, v72, v73
	v_cvt_pk_bf16_f32 v133, v74, v75
	ds_read_b64_tr_b16 v[72:73], v190 offset:31744
	ds_read_b64_tr_b16 v[74:75], v190 offset:32256
	v_mfma_f32_32x32x16_bf16 v[32:47], v[164:167], v[116:119], v[32:47]
	v_add_f32_e32 v92, v78, v92
	v_add_f32_e32 v92, v79, v92
	v_cvt_pk_bf16_f32 v134, v76, v77
	v_cvt_pk_bf16_f32 v135, v78, v79
	v_mfma_f32_32x32x16_bf16 v[48:63], v[148:151], v[96:99], v[48:63]
	s_mov_b64 s[62:63], 0x8190c00
	v_lshl_add_u64 v[76:77], v[214:215], 0, s[62:63]
	s_add_i32 s46, s47, s97
	s_mov_b32 s62, m0
	s_mov_b32 m0, s46
	s_nop 0
	global_load_lds_dwordx4 v[76:77], off
	s_mov_b32 m0, s62
	s_mov_b64 s[62:63], 0x80f1000
	v_lshl_add_u64 v[76:77], v[216:217], 0, s[62:63]
	s_add_i32 s46, s43, s70
	v_mfma_f32_32x32x16_bf16 v[32:47], v[152:155], v[96:99], v[32:47]
	s_mov_b32 s62, m0
	s_mov_b32 m0, s46
	s_nop 0
	global_load_lds_dwordx4 v[76:77], off
	s_mov_b32 m0, s62
	s_nop 4
	v_max_f32_e32 v76, v48, v49
	v_add_f32_e32 v243, v197, v92
	s_nop 2
	v_max3_f32 v77, v50, v51, v33
	v_max3_f32 v76, v76, v32, v34
	v_max3_f32 v76, v76, v35, v52
	v_max3_f32 v77, v77, v54, v55
	v_max3_f32 v76, v76, v53, v36
	v_max3_f32 v77, v77, v38, v39
	v_max3_f32 v76, v76, v37, v56
	v_max3_f32 v77, v77, v58, v59
	v_max3_f32 v76, v76, v57, v40
	v_max3_f32 v77, v77, v42, v43
	v_max3_f32 v76, v76, v41, v60
	v_max3_f32 v77, v77, v62, v63
	v_max3_f32 v76, v76, v61, v44
	v_max3_f32 v77, v77, v46, v47
	v_max3_f32 v76, v76, v45, v77
	v_mov_b32_e32 v77, v76
	s_nop 1
	v_permlane32_swap_b32_e32 v76, v77
	v_max_f32_e32 v76, v76, v77
	v_cmp_lt_f32_e32 vcc, s84, v76
	s_cmp_lg_u64 vcc, 0
	s_cselect_b64 s[62:63], -1, 0
	s_cbranch_vccnz .LBB0_283

; #define RESC() do { if (resc) { asm volatile("s_waitcnt lgkmcnt(0)" ::: "memory"); \
;       _Pragma("unroll") for (int d_ = 0; d_ < 2; ++d_) _Pragma("unroll") for (int r = 0; r < 16; ++r) o[d_][r] *= wsf[crow(r, hi)]; } } while (0)
; #define ROT() do { sl_prev = sl_cur; sl_cur = sl_next; sl_next = (sl_next == (NSLOT - 1) * SLOTB) ? 0 : sl_next + SLOTB; } while (0)
; #define ENDW(tt) do { if ((tt) + 3 < NT) { WAIT_BAR(2); } else if ((tt) + 2 < NT) { WAIT_BAR(1); } else { WAIT_BAR(0); } } while (0)
; template <int THRL> __device__ __forceinline__ void attn_unit(int b, int h, int qb, const bf16* Q, const bf16* __restrict__ K, const bf16* __restrict__ V, bf16* O, char* shm, bool first, int qb_next, bf16x8& qn0, bf16x8& qn1, bf16x8& qn2, bf16x8& qn3) {
;     ...
;     for (; t + 1 < NT; t += 2) {
;         STEP(pB0, pB1, pA0, pA1, t, (t + 3 < NT), (t + 1 < NT), (t + 1 < NT));         ENDW(t);     RESC(); ROT();
;         STEP(pA0, pA1, pB0, pB1, t + 1, (t + 4 < NT), (t + 2 < NT), (t + 2 < NT));     ENDW(t + 1); RESC(); ROT();
.LBB0_299:
	v_add_u32_e32 v192, s47, v240
	ds_read_b64_tr_b16 v[188:189], v192 offset:24576
	ds_read_b64_tr_b16 v[190:191], v192 offset:25088
	s_waitcnt lgkmcnt(11)
	v_mfma_f32_32x32x16_bf16 v[80:95], v[184:187], v[128:131], 0
	v_add_f32_e32 v64, v48, v49
	v_add_f32_e32 v64, v50, v64
	v_add_f32_e32 v64, v51, v64
	v_add_f32_e32 v64, v52, v64
	v_add_f32_e32 v64, v53, v64
	v_cvt_pk_bf16_f32 v144, v48, v49
	v_cvt_pk_bf16_f32 v145, v50, v51
	ds_read_b64_tr_b16 v[184:185], v192 offset:28672
	ds_read_b64_tr_b16 v[186:187], v192 offset:29184
	v_add_f32_e32 v48, v54, v64
	s_waitcnt lgkmcnt(12)
	v_mfma_f32_32x32x16_bf16 v[64:79], v[176:179], v[128:131], 0
	v_add_f32_e32 v48, v55, v48
	v_add_f32_e32 v48, v56, v48
	v_add_f32_e32 v132, v57, v48
	v_cvt_pk_bf16_f32 v146, v52, v53
	v_cvt_pk_bf16_f32 v147, v54, v55
	ds_read_b64_tr_b16 v[48:49], v192 offset:25600
	ds_read_b64_tr_b16 v[50:51], v192 offset:26112
	s_waitcnt lgkmcnt(11)
	v_mfma_f32_32x32x16_bf16 v[80:95], v[180:183], v[124:127], v[80:95]
	v_add_f32_e32 v52, v58, v132
	v_add_f32_e32 v52, v59, v52
	v_add_f32_e32 v52, v60, v52
	v_add_f32_e32 v132, v61, v52
	v_cvt_pk_bf16_f32 v140, v56, v57
	v_cvt_pk_bf16_f32 v141, v58, v59
	ds_read_b64_tr_b16 v[52:53], v192 offset:29696
	ds_read_b64_tr_b16 v[54:55], v192 offset:30208
	s_waitcnt lgkmcnt(12)
	v_mfma_f32_32x32x16_bf16 v[64:79], v[172:175], v[124:127], v[64:79]
	v_add_f32_e32 v56, v62, v132
	v_add_f32_e32 v56, v63, v56
	v_add_f32_e32 v56, v32, v56
	v_add_f32_e32 v132, v33, v56
	v_cvt_pk_bf16_f32 v142, v60, v61
	v_cvt_pk_bf16_f32 v143, v62, v63
	ds_read_b64_tr_b16 v[56:57], v192 offset:26624
	ds_read_b64_tr_b16 v[58:59], v192 offset:27136
	s_waitcnt lgkmcnt(13)
	v_mfma_f32_32x32x16_bf16 v[80:95], v[168:171], v[120:123], v[80:95]
	v_add_f32_e32 v60, v34, v132
	v_add_f32_e32 v60, v35, v60
	v_add_f32_e32 v60, v36, v60
	v_add_f32_e32 v60, v37, v60
	v_cvt_pk_bf16_f32 v136, v32, v33
	v_cvt_pk_bf16_f32 v137, v34, v35
	ds_read_b64_tr_b16 v[32:33], v192 offset:30720
	ds_read_b64_tr_b16 v[34:35], v192 offset:31232
	s_waitcnt lgkmcnt(14)
	v_mfma_f32_32x32x16_bf16 v[64:79], v[164:167], v[120:123], v[64:79]
	v_add_f32_e32 v60, v38, v60
	v_add_f32_e32 v60, v39, v60
	v_add_f32_e32 v60, v40, v60
	v_add_f32_e32 v60, v41, v60
	v_cvt_pk_bf16_f32 v138, v36, v37
	v_cvt_pk_bf16_f32 v139, v38, v39
	ds_read_b64_tr_b16 v[36:37], v192 offset:27648
	ds_read_b64_tr_b16 v[38:39], v192 offset:28160
	s_waitcnt lgkmcnt(14)
	v_mfma_f32_32x32x16_bf16 v[80:95], v[160:163], v[116:119], v[80:95]
	v_add_f32_e32 v60, v42, v60
	v_add_f32_e32 v60, v43, v60
	v_add_f32_e32 v60, v44, v60
	v_add_f32_e32 v60, v45, v60
	v_cvt_pk_bf16_f32 v132, v40, v41
	v_cvt_pk_bf16_f32 v133, v42, v43
	ds_read_b64_tr_b16 v[40:41], v192 offset:31744
	ds_read_b64_tr_b16 v[42:43], v192 offset:32256
	v_mfma_f32_32x32x16_bf16 v[64:79], v[156:159], v[116:119], v[64:79]
	v_add_f32_e32 v60, v46, v60
	v_add_f32_e32 v60, v47, v60
	v_cvt_pk_bf16_f32 v134, v44, v45
	v_cvt_pk_bf16_f32 v135, v46, v47
	v_mfma_f32_32x32x16_bf16 v[80:95], v[152:155], v[96:99], v[80:95]
	s_add_i32 s8, s64, 1
	s_cmp_ge_u32 s8, s42
	s_cselect_b64 s[60:61], -1, 0
	s_and_b64 vcc, exec, s[60:61]
	v_lshl_add_u64 v[218:219], v[214:215], 0, s[20:21]
	v_mfma_f32_32x32x16_bf16 v[64:79], v[148:151], v[96:99], v[64:79]
	s_cbranch_vccnz .LBB0_301
	s_mov_b64 s[8:9], 0x80f0c00
	v_lshl_add_u64 v[44:45], v[218:219], 0, s[8:9]
	s_add_i32 s8, s43, s97
	s_mov_b32 s9, m0
	s_mov_b32 m0, s8
	s_nop 0
	global_load_lds_dwordx4 v[44:45], off
	s_mov_b32 m0, s9

; #define RESC() do { if (resc) { asm volatile("s_waitcnt lgkmcnt(0)" ::: "memory"); \
;       _Pragma("unroll") for (int d_ = 0; d_ < 2; ++d_) _Pragma("unroll") for (int r = 0; r < 16; ++r) o[d_][r] *= wsf[crow(r, hi)]; } } while (0)
; #define ROT() do { sl_prev = sl_cur; sl_cur = sl_next; sl_next = (sl_next == (NSLOT - 1) * SLOTB) ? 0 : sl_next + SLOTB; } while (0)
; #define ENDW(tt) do { if ((tt) + 3 < NT) { WAIT_BAR(2); } else if ((tt) + 2 < NT) { WAIT_BAR(1); } else { WAIT_BAR(0); } } while (0)
; template <int THRL> __device__ __forceinline__ void attn_unit(int b, int h, int qb, const bf16* Q, const bf16* __restrict__ K, const bf16* __restrict__ V, bf16* O, char* shm, bool first, int qb_next, bf16x8& qn0, bf16x8& qn1, bf16x8& qn2, bf16x8& qn3) {
;     ...
;     for (; t + 1 < NT; t += 2) {
;         STEP(pB0, pB1, pA0, pA1, t, (t + 3 < NT), (t + 1 < NT), (t + 1 < NT));         ENDW(t);     RESC(); ROT();
;         STEP(pA0, pA1, pB0, pB1, t + 1, (t + 4 < NT), (t + 2 < NT), (t + 2 < NT));     ENDW(t + 1); RESC(); ROT();
.LBB0_308:
	v_add_u32_e32 v250, s43, v240
	ds_read_b64_tr_b16 v[196:197], v250 offset:24576
	ds_read_b64_tr_b16 v[198:199], v250 offset:25088
	s_waitcnt lgkmcnt(11)
	v_mfma_f32_32x32x16_bf16 v[48:63], v[184:187], v[128:131], 0
	v_add_f32_e32 v32, v80, v81
	v_add_f32_e32 v32, v82, v32
	v_add_f32_e32 v32, v83, v32
	v_add_f32_e32 v32, v84, v32
	v_add_f32_e32 v32, v85, v32
	v_cvt_pk_bf16_f32 v144, v80, v81
	v_cvt_pk_bf16_f32 v145, v82, v83
	ds_read_b64_tr_b16 v[192:193], v250 offset:28672
	ds_read_b64_tr_b16 v[194:195], v250 offset:29184
	v_add_f32_e32 v32, v86, v32
	v_add_f32_e32 v32, v87, v32
	v_add_f32_e32 v32, v88, v32
	v_add_f32_e32 v80, v89, v32
	s_waitcnt lgkmcnt(12)
	v_mfma_f32_32x32x16_bf16 v[32:47], v[176:179], v[128:131], 0
	v_cvt_pk_bf16_f32 v146, v84, v85
	v_cvt_pk_bf16_f32 v147, v86, v87
	ds_read_b64_tr_b16 v[188:189], v250 offset:25600
	ds_read_b64_tr_b16 v[190:191], v250 offset:26112
	s_waitcnt lgkmcnt(11)
	v_mfma_f32_32x32x16_bf16 v[48:63], v[180:183], v[124:127], v[48:63]
	v_add_f32_e32 v80, v90, v80
	v_add_f32_e32 v80, v91, v80
	v_add_f32_e32 v80, v92, v80
	v_add_f32_e32 v80, v93, v80
	v_cvt_pk_bf16_f32 v140, v88, v89
	v_cvt_pk_bf16_f32 v141, v90, v91
	ds_read_b64_tr_b16 v[88:89], v250 offset:29696
	ds_read_b64_tr_b16 v[90:91], v250 offset:30208
	s_waitcnt lgkmcnt(12)
	v_mfma_f32_32x32x16_bf16 v[32:47], v[172:175], v[124:127], v[32:47]
	v_add_f32_e32 v80, v94, v80
	v_add_f32_e32 v80, v95, v80
	v_add_f32_e32 v80, v64, v80
	v_add_f32_e32 v80, v65, v80
	v_cvt_pk_bf16_f32 v142, v92, v93
	v_cvt_pk_bf16_f32 v143, v94, v95
	ds_read_b64_tr_b16 v[84:85], v250 offset:26624
	ds_read_b64_tr_b16 v[86:87], v250 offset:27136
	s_waitcnt lgkmcnt(13)
	v_mfma_f32_32x32x16_bf16 v[48:63], v[168:171], v[120:123], v[48:63]
	v_add_f32_e32 v80, v66, v80
	v_add_f32_e32 v80, v67, v80
	v_add_f32_e32 v80, v68, v80
	v_add_f32_e32 v92, v69, v80
	v_cvt_pk_bf16_f32 v136, v64, v65
	v_cvt_pk_bf16_f32 v137, v66, v67
	ds_read_b64_tr_b16 v[80:81], v250 offset:30720
	ds_read_b64_tr_b16 v[82:83], v250 offset:31232
	s_waitcnt lgkmcnt(14)
	v_mfma_f32_32x32x16_bf16 v[32:47], v[164:167], v[120:123], v[32:47]
	v_add_f32_e32 v64, v70, v92
	v_add_f32_e32 v64, v71, v64
	v_add_f32_e32 v64, v72, v64
	v_add_f32_e32 v64, v73, v64
	v_cvt_pk_bf16_f32 v138, v68, v69
	v_cvt_pk_bf16_f32 v139, v70, v71
	ds_read_b64_tr_b16 v[68:69], v250 offset:27648
	ds_read_b64_tr_b16 v[70:71], v250 offset:28160
	s_waitcnt lgkmcnt(14)
	v_mfma_f32_32x32x16_bf16 v[48:63], v[160:163], v[116:119], v[48:63]
	v_add_f32_e32 v64, v74, v64
	v_add_f32_e32 v64, v75, v64
	v_add_f32_e32 v64, v76, v64
	v_add_f32_e32 v92, v77, v64
	v_cvt_pk_bf16_f32 v132, v72, v73
	v_cvt_pk_bf16_f32 v133, v74, v75
	ds_read_b64_tr_b16 v[64:65], v250 offset:31744
	ds_read_b64_tr_b16 v[66:67], v250 offset:32256
	v_mfma_f32_32x32x16_bf16 v[32:47], v[156:159], v[116:119], v[32:47]
	v_add_f32_e32 v72, v78, v92
	v_add_f32_e32 v72, v79, v72
	v_cvt_pk_bf16_f32 v134, v76, v77
	v_cvt_pk_bf16_f32 v135, v78, v79
	v_mfma_f32_32x32x16_bf16 v[48:63], v[152:155], v[96:99], v[48:63]
	s_add_i32 s68, s64, 2
	s_cmp_ge_u32 s68, s42
	s_cselect_b64 s[62:63], -1, 0
	s_and_b64 vcc, exec, s[62:63]
	v_mfma_f32_32x32x16_bf16 v[32:47], v[148:151], v[96:99], v[32:47]
	s_cbranch_vccnz .LBB0_310
	v_lshl_add_u64 v[74:75], v[218:219], 0, s[28:29]
	s_add_i32 s8, s46, s97
	s_mov_b32 s9, m0
	s_mov_b32 m0, s8
	s_nop 0
	global_load_lds_dwordx4 v[74:75], off
	s_mov_b32 m0, s9
